# v9 plus FF1 epilogue without redundant canonicalize max
# baseline (speedup 1.0000x reference)
.LBB0_714:
	s_andn2_b64 vcc, exec, s[38:39]
	s_cbranch_vccnz .LBB0_748
	v_mov_b32_e32 v130, s59
	ds_read_b64 v[130:131], v130
	v_cndmask_b32_e64 v132, 0, 1, s[4:5]
	v_cmp_ne_u32_e64 s[38:39], 1, v132
	s_andn2_b64 vcc, exec, s[4:5]
	s_waitcnt lgkmcnt(0)
	v_readfirstlane_b32 s11, v131
	v_readfirstlane_b32 s10, v130
	s_cbranch_vccnz .LBB0_717
	v_max_f32_e32 v126, 0, v126
	v_max_f32_e32 v122, 0, v122
	v_max_f32_e32 v127, 0, v127
	v_max_f32_e32 v123, 0, v123
	v_max_f32_e32 v128, 0, v128
	v_max_f32_e32 v124, 0, v124
	v_max_f32_e32 v129, 0, v129
	v_max_f32_e32 v125, 0, v125
	v_mul_f32_e32 v126, v126, v126
	v_mul_f32_e32 v122, v122, v122
	v_mul_f32_e32 v127, v127, v127
	v_mul_f32_e32 v123, v123, v123
	v_mul_f32_e32 v128, v128, v128
	v_mul_f32_e32 v124, v124, v124
	v_mul_f32_e32 v129, v129, v129
	v_mul_f32_e32 v125, v125, v125
.LBB0_717:
	s_nop 0
	v_lshl_add_u64 v[130:131], v[158:159], 1, s[10:11]
	s_mov_b64 s[10:11], 0xe000000
	v_lshl_add_u64 v[130:131], v[130:131], 0, s[10:11]
	v_mad_i64_i32 v[132:133], s[10:11], s63, v156, 0
	v_lshl_add_u64 v[132:133], v[132:133], 1, v[130:131]
	s_and_b64 vcc, exec, s[38:39]
	v_cvt_pk_bf16_f32 v126, v126, v127
	v_cvt_pk_bf16_f32 v127, v128, v129
	v_cvt_pk_bf16_f32 v128, v122, v123
	v_cvt_pk_bf16_f32 v129, v124, v125
	global_store_dwordx4 v[132:133], v[126:129], off
	s_cbranch_vccnz .LBB0_719
	v_max_f32_e32 v118, 0, v118
	v_max_f32_e32 v114, 0, v114
	v_max_f32_e32 v119, 0, v119
	v_max_f32_e32 v115, 0, v115
	v_max_f32_e32 v120, 0, v120
	v_max_f32_e32 v116, 0, v116
	v_max_f32_e32 v121, 0, v121
	v_max_f32_e32 v117, 0, v117
	v_mul_f32_e32 v118, v118, v118
	v_mul_f32_e32 v114, v114, v114
	v_mul_f32_e32 v119, v119, v119
	v_mul_f32_e32 v115, v115, v115
	v_mul_f32_e32 v120, v120, v120
	v_mul_f32_e32 v116, v116, v116
	v_mul_f32_e32 v121, v121, v121
	v_mul_f32_e32 v117, v117, v117
.LBB0_719:
	s_and_b64 vcc, exec, s[38:39]
	v_cvt_pk_bf16_f32 v118, v118, v119
	v_cvt_pk_bf16_f32 v119, v120, v121
	v_cvt_pk_bf16_f32 v120, v114, v115
	v_cvt_pk_bf16_f32 v121, v116, v117
	global_store_dwordx4 v[132:133], v[118:121], off offset:256
	s_cbranch_vccnz .LBB0_721
	v_max_f32_e32 v110, 0, v110
	v_max_f32_e32 v106, 0, v106
	v_max_f32_e32 v111, 0, v111
	v_max_f32_e32 v107, 0, v107
	v_max_f32_e32 v112, 0, v112
	v_max_f32_e32 v108, 0, v108
	v_max_f32_e32 v113, 0, v113
	v_max_f32_e32 v109, 0, v109
	v_mul_f32_e32 v110, v110, v110
	v_mul_f32_e32 v106, v106, v106
	v_mul_f32_e32 v111, v111, v111
	v_mul_f32_e32 v107, v107, v107
	v_mul_f32_e32 v112, v112, v112
	v_mul_f32_e32 v108, v108, v108
	v_mul_f32_e32 v113, v113, v113
	v_mul_f32_e32 v109, v109, v109
.LBB0_721:
	v_mad_i64_i32 v[114:115], s[10:11], s63, v170, 0
	v_lshl_add_u64 v[114:115], v[114:115], 1, v[130:131]
	s_and_b64 vcc, exec, s[38:39]
	v_cvt_pk_bf16_f32 v110, v110, v111
	v_cvt_pk_bf16_f32 v111, v112, v113
	v_cvt_pk_bf16_f32 v112, v106, v107
	v_cvt_pk_bf16_f32 v113, v108, v109
	global_store_dwordx4 v[114:115], v[110:113], off
	s_cbranch_vccnz .LBB0_723
	v_max_f32_e32 v102, 0, v102
	v_max_f32_e32 v98, 0, v98
	v_max_f32_e32 v103, 0, v103
	v_max_f32_e32 v99, 0, v99
	v_max_f32_e32 v104, 0, v104
	v_max_f32_e32 v100, 0, v100
	v_max_f32_e32 v105, 0, v105
	v_max_f32_e32 v101, 0, v101
	v_mul_f32_e32 v102, v102, v102
	v_mul_f32_e32 v98, v98, v98
	v_mul_f32_e32 v103, v103, v103
	v_mul_f32_e32 v99, v99, v99
	v_mul_f32_e32 v104, v104, v104
	v_mul_f32_e32 v100, v100, v100
	v_mul_f32_e32 v105, v105, v105
	v_mul_f32_e32 v101, v101, v101
.LBB0_723:
	s_and_b64 vcc, exec, s[38:39]
	v_cvt_pk_bf16_f32 v102, v102, v103
	v_cvt_pk_bf16_f32 v103, v104, v105
	v_cvt_pk_bf16_f32 v104, v98, v99
	v_cvt_pk_bf16_f32 v105, v100, v101
	global_store_dwordx4 v[114:115], v[102:105], off offset:256
	s_cbranch_vccnz .LBB0_725
	v_max_f32_e32 v94, 0, v94
	v_max_f32_e32 v90, 0, v90
	v_max_f32_e32 v95, 0, v95
	v_max_f32_e32 v91, 0, v91
	v_max_f32_e32 v96, 0, v96
	v_max_f32_e32 v92, 0, v92
	v_max_f32_e32 v97, 0, v97
	v_max_f32_e32 v93, 0, v93
	v_mul_f32_e32 v94, v94, v94
	v_mul_f32_e32 v90, v90, v90
	v_mul_f32_e32 v95, v95, v95
	v_mul_f32_e32 v91, v91, v91
	v_mul_f32_e32 v96, v96, v96
	v_mul_f32_e32 v92, v92, v92
	v_mul_f32_e32 v97, v97, v97
	v_mul_f32_e32 v93, v93, v93
.LBB0_725:
	v_mad_i64_i32 v[98:99], s[10:11], s63, v168, 0
	v_lshl_add_u64 v[98:99], v[98:99], 1, v[130:131]
	s_and_b64 vcc, exec, s[38:39]
	v_cvt_pk_bf16_f32 v94, v94, v95
	v_cvt_pk_bf16_f32 v95, v96, v97
	v_cvt_pk_bf16_f32 v96, v90, v91
	v_cvt_pk_bf16_f32 v97, v92, v93
	global_store_dwordx4 v[98:99], v[94:97], off
	s_cbranch_vccnz .LBB0_727
	v_max_f32_e32 v86, 0, v86
	v_max_f32_e32 v82, 0, v82
	v_max_f32_e32 v87, 0, v87
	v_max_f32_e32 v83, 0, v83
	v_max_f32_e32 v88, 0, v88
	v_max_f32_e32 v84, 0, v84
	v_max_f32_e32 v89, 0, v89
	v_max_f32_e32 v85, 0, v85
	v_mul_f32_e32 v86, v86, v86
	v_mul_f32_e32 v82, v82, v82
	v_mul_f32_e32 v87, v87, v87
	v_mul_f32_e32 v83, v83, v83
	v_mul_f32_e32 v88, v88, v88
	v_mul_f32_e32 v84, v84, v84
	v_mul_f32_e32 v89, v89, v89
	v_mul_f32_e32 v85, v85, v85
.LBB0_727:
	s_and_b64 vcc, exec, s[38:39]
	v_cvt_pk_bf16_f32 v86, v86, v87
	v_cvt_pk_bf16_f32 v87, v88, v89
	v_cvt_pk_bf16_f32 v88, v82, v83
	v_cvt_pk_bf16_f32 v89, v84, v85
	global_store_dwordx4 v[98:99], v[86:89], off offset:256
	s_cbranch_vccnz .LBB0_729
	v_max_f32_e32 v78, 0, v78
	v_max_f32_e32 v74, 0, v74
	v_max_f32_e32 v79, 0, v79
	v_max_f32_e32 v75, 0, v75
	v_max_f32_e32 v80, 0, v80
	v_max_f32_e32 v76, 0, v76
	v_max_f32_e32 v81, 0, v81
	v_max_f32_e32 v77, 0, v77
	v_mul_f32_e32 v78, v78, v78
	v_mul_f32_e32 v74, v74, v74
	v_mul_f32_e32 v79, v79, v79
	v_mul_f32_e32 v75, v75, v75
	v_mul_f32_e32 v80, v80, v80
	v_mul_f32_e32 v76, v76, v76
	v_mul_f32_e32 v81, v81, v81
	v_mul_f32_e32 v77, v77, v77
.LBB0_729:
	v_mad_i64_i32 v[82:83], s[10:11], s63, v166, 0
	v_lshl_add_u64 v[82:83], v[82:83], 1, v[130:131]
	s_and_b64 vcc, exec, s[38:39]
	v_cvt_pk_bf16_f32 v78, v78, v79
	v_cvt_pk_bf16_f32 v79, v80, v81
	v_cvt_pk_bf16_f32 v80, v74, v75
	v_cvt_pk_bf16_f32 v81, v76, v77
	global_store_dwordx4 v[82:83], v[78:81], off
	s_cbranch_vccnz .LBB0_731
	v_max_f32_e32 v70, 0, v70
	v_max_f32_e32 v66, 0, v66
	v_max_f32_e32 v71, 0, v71
	v_max_f32_e32 v67, 0, v67
	v_max_f32_e32 v72, 0, v72
	v_max_f32_e32 v68, 0, v68
	v_max_f32_e32 v73, 0, v73
	v_max_f32_e32 v69, 0, v69
	v_mul_f32_e32 v70, v70, v70
	v_mul_f32_e32 v66, v66, v66
	v_mul_f32_e32 v71, v71, v71
	v_mul_f32_e32 v67, v67, v67
	v_mul_f32_e32 v72, v72, v72
	v_mul_f32_e32 v68, v68, v68
	v_mul_f32_e32 v73, v73, v73
	v_mul_f32_e32 v69, v69, v69
.LBB0_731:
	s_and_b64 vcc, exec, s[38:39]
	v_cvt_pk_bf16_f32 v70, v70, v71
	v_cvt_pk_bf16_f32 v71, v72, v73
	v_cvt_pk_bf16_f32 v72, v66, v67
	v_cvt_pk_bf16_f32 v73, v68, v69
	global_store_dwordx4 v[82:83], v[70:73], off offset:256
	s_cbranch_vccnz .LBB0_733
	v_max_f32_e32 v62, 0, v62
	v_max_f32_e32 v58, 0, v58
	v_max_f32_e32 v63, 0, v63
	v_max_f32_e32 v59, 0, v59
	v_max_f32_e32 v64, 0, v64
	v_max_f32_e32 v60, 0, v60
	v_max_f32_e32 v65, 0, v65
	v_max_f32_e32 v61, 0, v61
	v_mul_f32_e32 v62, v62, v62
	v_mul_f32_e32 v58, v58, v58
	v_mul_f32_e32 v63, v63, v63
	v_mul_f32_e32 v59, v59, v59
	v_mul_f32_e32 v64, v64, v64
	v_mul_f32_e32 v60, v60, v60
	v_mul_f32_e32 v65, v65, v65
	v_mul_f32_e32 v61, v61, v61
.LBB0_733:
	v_mad_i64_i32 v[66:67], s[10:11], s63, v164, 0
	v_lshl_add_u64 v[66:67], v[66:67], 1, v[130:131]
	s_and_b64 vcc, exec, s[38:39]
	v_cvt_pk_bf16_f32 v62, v62, v63
	v_cvt_pk_bf16_f32 v63, v64, v65
	v_cvt_pk_bf16_f32 v64, v58, v59
	v_cvt_pk_bf16_f32 v65, v60, v61
	global_store_dwordx4 v[66:67], v[62:65], off
	s_cbranch_vccnz .LBB0_735
	v_max_f32_e32 v54, 0, v54
	v_max_f32_e32 v50, 0, v50
	v_max_f32_e32 v55, 0, v55
	v_max_f32_e32 v51, 0, v51
	v_max_f32_e32 v56, 0, v56
	v_max_f32_e32 v52, 0, v52
	v_max_f32_e32 v57, 0, v57
	v_max_f32_e32 v53, 0, v53
	v_mul_f32_e32 v54, v54, v54
	v_mul_f32_e32 v50, v50, v50
	v_mul_f32_e32 v55, v55, v55
	v_mul_f32_e32 v51, v51, v51
	v_mul_f32_e32 v56, v56, v56
	v_mul_f32_e32 v52, v52, v52
	v_mul_f32_e32 v57, v57, v57
	v_mul_f32_e32 v53, v53, v53
.LBB0_735:
	s_and_b64 vcc, exec, s[38:39]
	v_cvt_pk_bf16_f32 v54, v54, v55
	v_cvt_pk_bf16_f32 v55, v56, v57
	v_cvt_pk_bf16_f32 v56, v50, v51
	v_cvt_pk_bf16_f32 v57, v52, v53
	global_store_dwordx4 v[66:67], v[54:57], off offset:256
	s_cbranch_vccnz .LBB0_737
	v_max_f32_e32 v46, 0, v46
	v_max_f32_e32 v42, 0, v42
	v_max_f32_e32 v47, 0, v47
	v_max_f32_e32 v43, 0, v43
	v_max_f32_e32 v48, 0, v48
	v_max_f32_e32 v44, 0, v44
	v_max_f32_e32 v49, 0, v49
	v_max_f32_e32 v45, 0, v45
	v_mul_f32_e32 v46, v46, v46
	v_mul_f32_e32 v42, v42, v42
	v_mul_f32_e32 v47, v47, v47
	v_mul_f32_e32 v43, v43, v43
	v_mul_f32_e32 v48, v48, v48
	v_mul_f32_e32 v44, v44, v44
	v_mul_f32_e32 v49, v49, v49
	v_mul_f32_e32 v45, v45, v45
.LBB0_737:
	v_mad_i64_i32 v[50:51], s[10:11], s63, v162, 0
	v_lshl_add_u64 v[50:51], v[50:51], 1, v[130:131]
	s_and_b64 vcc, exec, s[38:39]
	v_cvt_pk_bf16_f32 v46, v46, v47
	v_cvt_pk_bf16_f32 v47, v48, v49
	v_cvt_pk_bf16_f32 v48, v42, v43
	v_cvt_pk_bf16_f32 v49, v44, v45
	global_store_dwordx4 v[50:51], v[46:49], off
	s_cbranch_vccnz .LBB0_739
	v_max_f32_e32 v38, 0, v38
	v_max_f32_e32 v34, 0, v34
	v_max_f32_e32 v39, 0, v39
	v_max_f32_e32 v35, 0, v35
	v_max_f32_e32 v40, 0, v40
	v_max_f32_e32 v36, 0, v36
	v_max_f32_e32 v41, 0, v41
	v_max_f32_e32 v37, 0, v37
	v_mul_f32_e32 v38, v38, v38
	v_mul_f32_e32 v34, v34, v34
	v_mul_f32_e32 v39, v39, v39
	v_mul_f32_e32 v35, v35, v35
	v_mul_f32_e32 v40, v40, v40
	v_mul_f32_e32 v36, v36, v36
	v_mul_f32_e32 v41, v41, v41
	v_mul_f32_e32 v37, v37, v37
.LBB0_739:
	s_and_b64 vcc, exec, s[38:39]
	v_cvt_pk_bf16_f32 v38, v38, v39
	v_cvt_pk_bf16_f32 v39, v40, v41
	v_cvt_pk_bf16_f32 v40, v34, v35
	v_cvt_pk_bf16_f32 v41, v36, v37
	global_store_dwordx4 v[50:51], v[38:41], off offset:256
	s_cbranch_vccnz .LBB0_741
	v_max_f32_e32 v30, 0, v30
	v_max_f32_e32 v26, 0, v26
	v_max_f32_e32 v31, 0, v31
	v_max_f32_e32 v27, 0, v27
	v_max_f32_e32 v32, 0, v32
	v_max_f32_e32 v28, 0, v28
	v_max_f32_e32 v33, 0, v33
	v_max_f32_e32 v29, 0, v29
	v_mul_f32_e32 v30, v30, v30
	v_mul_f32_e32 v26, v26, v26
	v_mul_f32_e32 v31, v31, v31
	v_mul_f32_e32 v27, v27, v27
	v_mul_f32_e32 v32, v32, v32
	v_mul_f32_e32 v28, v28, v28
	v_mul_f32_e32 v33, v33, v33
	v_mul_f32_e32 v29, v29, v29
.LBB0_741:
	v_mad_i64_i32 v[34:35], s[10:11], s63, v160, 0
	v_lshl_add_u64 v[34:35], v[34:35], 1, v[130:131]
	s_and_b64 vcc, exec, s[38:39]
	v_cvt_pk_bf16_f32 v30, v30, v31
	v_cvt_pk_bf16_f32 v31, v32, v33
	v_cvt_pk_bf16_f32 v32, v26, v27
	v_cvt_pk_bf16_f32 v33, v28, v29
	global_store_dwordx4 v[34:35], v[30:33], off
	s_cbranch_vccnz .LBB0_743
	v_max_f32_e32 v22, 0, v22
	v_max_f32_e32 v18, 0, v18
	v_max_f32_e32 v23, 0, v23
	v_max_f32_e32 v19, 0, v19
	v_max_f32_e32 v24, 0, v24
	v_max_f32_e32 v20, 0, v20
	v_max_f32_e32 v25, 0, v25
	v_max_f32_e32 v21, 0, v21
	v_mul_f32_e32 v22, v22, v22
	v_mul_f32_e32 v18, v18, v18
	v_mul_f32_e32 v23, v23, v23
	v_mul_f32_e32 v19, v19, v19
	v_mul_f32_e32 v24, v24, v24
	v_mul_f32_e32 v20, v20, v20
	v_mul_f32_e32 v25, v25, v25
	v_mul_f32_e32 v21, v21, v21
.LBB0_743:
	s_and_b64 vcc, exec, s[38:39]
	v_cvt_pk_bf16_f32 v22, v22, v23
	v_cvt_pk_bf16_f32 v23, v24, v25
	v_cvt_pk_bf16_f32 v24, v18, v19
	v_cvt_pk_bf16_f32 v25, v20, v21
	global_store_dwordx4 v[34:35], v[22:25], off offset:256
	s_cbranch_vccnz .LBB0_745
	v_max_f32_e32 v14, 0, v14
	v_max_f32_e32 v10, 0, v10
	v_max_f32_e32 v15, 0, v15
	v_max_f32_e32 v11, 0, v11
	v_max_f32_e32 v16, 0, v16
	v_max_f32_e32 v12, 0, v12
	v_max_f32_e32 v17, 0, v17
	v_max_f32_e32 v13, 0, v13
	v_mul_f32_e32 v14, v14, v14
	v_mul_f32_e32 v10, v10, v10
	v_mul_f32_e32 v15, v15, v15
	v_mul_f32_e32 v11, v11, v11
	v_mul_f32_e32 v16, v16, v16
	v_mul_f32_e32 v12, v12, v12
	v_mul_f32_e32 v17, v17, v17
	v_mul_f32_e32 v13, v13, v13
.LBB0_745:
	v_add_u32_e32 v18, 0xb0, v156
	v_mad_i64_i32 v[18:19], s[10:11], s63, v18, 0
	v_lshl_add_u64 v[18:19], v[18:19], 1, v[130:131]
	s_and_b64 vcc, exec, s[38:39]
	v_cvt_pk_bf16_f32 v14, v14, v15
	v_cvt_pk_bf16_f32 v15, v16, v17
	v_cvt_pk_bf16_f32 v16, v10, v11
	v_cvt_pk_bf16_f32 v17, v12, v13
	global_store_dwordx4 v[18:19], v[14:17], off
	s_cbranch_vccnz .LBB0_747
	v_max_f32_e32 v6, 0, v6
	v_max_f32_e32 v2, 0, v2
	v_max_f32_e32 v7, 0, v7
	v_max_f32_e32 v3, 0, v3
	v_max_f32_e32 v8, 0, v8
	v_max_f32_e32 v4, 0, v4
	v_max_f32_e32 v9, 0, v9
	v_max_f32_e32 v5, 0, v5
	v_mul_f32_e32 v6, v6, v6
	v_mul_f32_e32 v2, v2, v2
	v_mul_f32_e32 v7, v7, v7
	v_mul_f32_e32 v3, v3, v3
	v_mul_f32_e32 v8, v8, v8
	v_mul_f32_e32 v4, v4, v4
	v_mul_f32_e32 v9, v9, v9
	v_mul_f32_e32 v5, v5, v5
